# NSA scan loops: posmax scalar load uses an SGPR offset instead of a 64-bit add/addc address
# baseline (speedup 1.0000x reference)
;   DI bool farj(int j) const { return (j * 64 + 63 < q0) && (pqmin - posmax[j] >= 799); }
;   DI bool farj(int j) const { return (j * 64 + 63 < q0) && (pqmin - posmax[j] >= 799); }
;   DI int next(int t) const { for (int j = t + 1; j < 128; ++j) if (inu(j) && farj(j)) return j; return -1; }
;   DI bool inu(int j) const {
;     unsigned long long a = (ulo >> (j & 63)) & (j < 64 ? 1ull : 0ull);
;     unsigned long long b = (uhi >> (j & 63)) & (j >= 64 ? 1ull : 0ull);
;     return (a | b) != 0ull;
;   }
;   DI bool mine(int j) const {
;     unsigned long long a = (mlo >> (j & 63)) & (j < 64 ? 1ull : 0ull);
;     unsigned long long b = (mhi >> (j & 63)) & (j >= 64 ? 1ull : 0ull);
;     return (a | b) != 0ull;
;   }
;   DI int next(int t) const { for (int j = t + 1; j < 128; ++j) if (inu(j) && !farj(j)) return j; return -1; }
.LBB0_674:
	s_add_i32 s64, s54, 1
	s_cmp_lt_i32 s54, 63
	s_cselect_b64 s[12:13], s[14:15], s[52:53]
	s_lshr_b64 s[12:13], s[12:13], s64
	s_and_b32 s12, s12, 1
	s_cmp_eq_u32 s12, 0
	s_cselect_b64 vcc, -1, 0
	s_mov_b64 s[12:13], -1
	s_mov_b64 s[36:37], -1
	s_cbranch_vccnz .LBB0_677
	s_cmp_lt_i32 s47, s34
	s_mov_b64 s[36:37], 0
	s_cbranch_scc0 .LBB0_677
	s_lshl_b32 s36, s64, 2
	s_load_dword s36, s[44:45], s36
	s_waitcnt vmcnt(0) lgkmcnt(0)
	v_subrev_u32_e32 v0, s36, v151
	v_cmp_lt_i32_e64 s[36:37], s93, v0

;   DI bool farj(int j) const { return (j * 64 + 63 < q0) && (pqmin - posmax[j] >= 799); }
;   DI int next(int t) const { for (int j = t + 1; j < 128; ++j) if (inu(j) && !farj(j)) return j; return -1; }
;   DI bool farj(int j) const { return (j * 64 + 63 < q0) && (pqmin - posmax[j] >= 799); }
;   DI bool inu(int j) const {
;     unsigned long long a = (ulo >> (j & 63)) & (j < 64 ? 1ull : 0ull);
;     unsigned long long b = (uhi >> (j & 63)) & (j >= 64 ? 1ull : 0ull);
;     return (a | b) != 0ull;
;   }
;   DI bool mine(int j) const {
;     unsigned long long a = (mlo >> (j & 63)) & (j < 64 ? 1ull : 0ull);
;     unsigned long long b = (mhi >> (j & 63)) & (j >= 64 ? 1ull : 0ull);
;     return (a | b) != 0ull;
;   }
;   DI int next(int t) const { for (int j = t + 1; j < 128; ++j) if (inu(j) && farj(j)) return j; return -1; }
.LBB0_767:
	s_add_i32 s64, s36, 1
	s_cmp_lt_i32 s36, 63
	s_cselect_b64 s[6:7], s[14:15], s[52:53]
	s_lshr_b64 s[6:7], s[6:7], s64
	s_and_b32 s6, s6, 1
	s_cmp_eq_u32 s6, 0
	s_cselect_b64 s[6:7], -1, 0
	s_and_b64 vcc, exec, s[6:7]
	s_cbranch_vccnz .LBB0_770
	s_cmp_ge_i32 s27, s34
	s_cselect_b64 s[6:7], -1, 0
	s_cmp_lt_i32 s27, s34
	s_cbranch_scc0 .LBB0_770
	s_lshl_b32 s6, s64, 2
	s_load_dword s6, s[44:45], s6
	s_waitcnt vmcnt(0) lgkmcnt(0)
	v_subrev_u32_e32 v0, s6, v151
	v_cmp_gt_i32_e64 s[6:7], s89, v0
